# grid barrier: members poll the top-level generation word directly (one memory round trip less per barrier); leaders no longer republish per XCD
# speedup vs baseline: 1.0038x; 1.0038x over previous
;     __device__ __forceinline__ const char* b(const Unit& u) const { return (const char*)Bt + (size_t)u.pn * 2 * hB() + (size_t)(u.pm >> gshift) * goff; }
;     __device__ __forceinline__ const char* b(const Unit& u) const { return (const char*)Bt + (size_t)((u.pn >> 4) * 4096 + (u.pn & 15) * 16) * 1024 * 2 + (size_t)(u.pm >> 1) * 512; }
;     __device__ __forceinline__ const char* b(const Unit& u) const { return (const char*)Bt + ((size_t)(((u.pm >> 4) * 1024 + u.pn * 256) * 16 + (u.pm & 15)) * 512) * 2; }
; __device__ __forceinline__ unsigned xb_ld(unsigned* p)              { return __hip_atomic_load(p, __ATOMIC_RELAXED, __HIP_MEMORY_SCOPE_AGENT); }
; __device__ __forceinline__ unsigned xb_add(unsigned* p, unsigned v) { return __hip_atomic_fetch_add(p, v, __ATOMIC_RELAXED, __HIP_MEMORY_SCOPE_AGENT); }
; #define XB_SPIN(cond, bar) do { unsigned _sp = 0; while (cond) { __builtin_amdgcn_s_sleep(1); \
;     if ((++_sp & 255u) == 0u) { if (xb_ld(&(bar)[XB_TMO])) break; if (_sp > XB_SPIN_CAP) { atomicAdd(&(bar)[XB_TMO], 1u); break; } } } } while (0)
; __device__ __forceinline__ void xcd_barrier(const XcdBarrier& b, const int wave) {
;     ...
;         const unsigned old = xb_add(&bar[XB_XSUB(b.x)], 1u);
;         const unsigned gen = old / nloc;
;         if (old + 1u == (gen + 1u) * nloc) {
;             __builtin_amdgcn_fence(__ATOMIC_RELEASE, "agent");
;             asm volatile("s_waitcnt vmcnt(0)" ::: "memory");
;             const unsigned og = xb_add(&bar[XB_TOP], 1u);
;             const unsigned tg = og / nx;
;             if (og + 1u == (tg + 1u) * nx) xb_add(&bar[XB_TOPGEN], 1u);
;             else XB_SPIN(xb_ld(&bar[XB_TOPGEN]) == tg, bar);
;             __builtin_amdgcn_fence(__ATOMIC_ACQUIRE, "agent");
;             xb_add(&bar[XB_XGEN(b.x)], 1u);
;             asm volatile("s_waitcnt vmcnt(0)" ::: "memory");
;         } else {
;             XB_SPIN(xb_ld(&bar[XB_XGEN(b.x)]) == gen, bar);
.LBB0_128:
	s_or_b64 exec, exec, s[10:11]
	v_cvt_f32_u32_e32 v4, v2
	s_waitcnt vmcnt(0)
	v_readfirstlane_b32 s8, v3
	v_sub_u32_e32 v3, 0, v2
	v_rcp_iflag_f32_e32 v4, v4
	v_add_u32_e32 v5, s8, v1
	v_mul_f32_e32 v4, 0x4f7ffffe, v4
	v_cvt_u32_f32_e32 v4, v4
	v_mul_lo_u32 v1, v3, v4
	v_mul_hi_u32 v1, v4, v1
	v_add_u32_e32 v1, v4, v1
	v_mul_hi_u32 v1, v5, v1
	v_mul_lo_u32 v3, v1, v2
	v_sub_u32_e32 v3, v5, v3
	v_add_u32_e32 v4, 1, v1
	v_cmp_ge_u32_e32 vcc, v3, v2
	s_nop 1
	v_cndmask_b32_e32 v1, v1, v4, vcc
	v_sub_u32_e32 v4, v3, v2
	v_cndmask_b32_e32 v3, v3, v4, vcc
	v_add_u32_e32 v4, 1, v1
	v_cmp_ge_u32_e32 vcc, v3, v2
	v_add_u32_e32 v3, 1, v5
	s_nop 0
	v_cndmask_b32_e32 v1, v1, v4, vcc
	v_mul_lo_u32 v4, v2, v1
	v_add_u32_e32 v2, v4, v2
	v_cmp_ne_u32_e32 vcc, v3, v2
	s_and_saveexec_b64 s[8:9], vcc
	s_xor_b64 s[8:9], exec, s[8:9]
	s_cbranch_execz .LBB0_142
	s_waitcnt lgkmcnt(0)
	s_add_u32 s16, s94, 0x7500
	s_addc_u32 s17, s95, 0
	v_mov_b32_e32 v0, 0
	global_load_dword v0, v0, s[16:17] sc1
	s_waitcnt vmcnt(0)
	v_cmp_eq_u32_e32 vcc, v0, v1
	s_and_saveexec_b64 s[10:11], vcc
	s_cbranch_execz .LBB0_141
	s_add_u32 s12, s94, 0x4200
	s_addc_u32 s13, s95, 0
	s_mov_b32 s14, 1
	s_mov_b64 s[18:19], 0
	v_mov_b32_e32 v0, 0
	s_branch .LBB0_132

;     __device__ __forceinline__ const char* b(const Unit& u) const { return (const char*)Bt + (size_t)u.pn * 2 * hB() + (size_t)(u.pm >> gshift) * goff; }
;     __device__ __forceinline__ const char* b(const Unit& u) const { return (const char*)Bt + (size_t)((u.pn >> 4) * 4096 + (u.pn & 15) * 16) * 1024 * 2 + (size_t)(u.pm >> 1) * 512; }
;     __device__ __forceinline__ const char* b(const Unit& u) const { return (const char*)Bt + ((size_t)(((u.pm >> 4) * 1024 + u.pn * 256) * 16 + (u.pm & 15)) * 512) * 2; }
; __device__ __forceinline__ unsigned xb_add(unsigned* p, unsigned v) { return __hip_atomic_fetch_add(p, v, __ATOMIC_RELAXED, __HIP_MEMORY_SCOPE_AGENT); }
; __device__ __forceinline__ void xcd_barrier(const XcdBarrier& b, const int wave) {
;     ...
;             __builtin_amdgcn_fence(__ATOMIC_ACQUIRE, "agent");
;             xb_add(&bar[XB_XGEN(b.x)], 1u);
.LBB0_159:
	s_or_b64 exec, exec, s[8:9]
	s_mov_b64 s[8:9], exec
	v_mbcnt_lo_u32_b32 v0, s8, 0
	v_mbcnt_hi_u32_b32 v0, s9, v0
	v_cmp_eq_u32_e32 vcc, 0, v0
	s_waitcnt vmcnt(0)
	buffer_inv sc1
	s_and_saveexec_b64 s[10:11], vcc
	s_cbranch_execz .LBB0_161
	s_bcnt1_i32_b64 s8, s[8:9]
	v_mov_b32_e32 v0, 0x2000
	v_mov_b32_e32 v1, s8
.LBB0_161:
	s_or_b64 exec, exec, s[10:11]
	s_waitcnt vmcnt(0)

;     __device__ __forceinline__ const char* b(const Unit& u) const { return (const char*)Bt + (size_t)u.pn * 2 * hB() + (size_t)(u.pm >> gshift) * goff; }
;     __device__ __forceinline__ const char* b(const Unit& u) const { return (const char*)Bt + (size_t)((u.pn >> 4) * 4096 + (u.pn & 15) * 16) * 1024 * 2 + (size_t)(u.pm >> 1) * 512; }
;     __device__ __forceinline__ const char* b(const Unit& u) const { return (const char*)Bt + ((size_t)(((u.pm >> 4) * 1024 + u.pn * 256) * 16 + (u.pm & 15)) * 512) * 2; }
; __device__ __forceinline__ unsigned xb_ld(unsigned* p)              { return __hip_atomic_load(p, __ATOMIC_RELAXED, __HIP_MEMORY_SCOPE_AGENT); }
; __device__ __forceinline__ unsigned xb_add(unsigned* p, unsigned v) { return __hip_atomic_fetch_add(p, v, __ATOMIC_RELAXED, __HIP_MEMORY_SCOPE_AGENT); }
; #define XB_SPIN(cond, bar) do { unsigned _sp = 0; while (cond) { __builtin_amdgcn_s_sleep(1); \
;     if ((++_sp & 255u) == 0u) { if (xb_ld(&(bar)[XB_TMO])) break; if (_sp > XB_SPIN_CAP) { atomicAdd(&(bar)[XB_TMO], 1u); break; } } } } while (0)
; __device__ __forceinline__ void xcd_barrier(const XcdBarrier& b, const int wave) {
;     ...
;         const unsigned old = xb_add(&bar[XB_XSUB(b.x)], 1u);
;         const unsigned gen = old / nloc;
;         if (old + 1u == (gen + 1u) * nloc) {
;             __builtin_amdgcn_fence(__ATOMIC_RELEASE, "agent");
;             asm volatile("s_waitcnt vmcnt(0)" ::: "memory");
;             const unsigned og = xb_add(&bar[XB_TOP], 1u);
;             const unsigned tg = og / nx;
;             if (og + 1u == (tg + 1u) * nx) xb_add(&bar[XB_TOPGEN], 1u);
;             else XB_SPIN(xb_ld(&bar[XB_TOPGEN]) == tg, bar);
;             __builtin_amdgcn_fence(__ATOMIC_ACQUIRE, "agent");
;             xb_add(&bar[XB_XGEN(b.x)], 1u);
;             asm volatile("s_waitcnt vmcnt(0)" ::: "memory");
;         } else {
;             XB_SPIN(xb_ld(&bar[XB_XGEN(b.x)]) == gen, bar);
.LBB0_304:
	s_or_b64 exec, exec, s[8:9]
	v_cvt_f32_u32_e32 v4, v2
	s_waitcnt vmcnt(0)
	v_readfirstlane_b32 s6, v3
	v_sub_u32_e32 v3, 0, v2
	v_rcp_iflag_f32_e32 v4, v4
	v_add_u32_e32 v5, s6, v1
	v_mul_f32_e32 v4, 0x4f7ffffe, v4
	v_cvt_u32_f32_e32 v4, v4
	v_mul_lo_u32 v1, v3, v4
	v_mul_hi_u32 v1, v4, v1
	v_add_u32_e32 v1, v4, v1
	v_mul_hi_u32 v1, v5, v1
	v_mul_lo_u32 v3, v1, v2
	v_sub_u32_e32 v3, v5, v3
	v_add_u32_e32 v4, 1, v1
	v_cmp_ge_u32_e32 vcc, v3, v2
	s_nop 1
	v_cndmask_b32_e32 v1, v1, v4, vcc
	v_sub_u32_e32 v4, v3, v2
	v_cndmask_b32_e32 v3, v3, v4, vcc
	v_add_u32_e32 v4, 1, v1
	v_cmp_ge_u32_e32 vcc, v3, v2
	v_add_u32_e32 v3, 1, v5
	s_nop 0
	v_cndmask_b32_e32 v1, v1, v4, vcc
	v_mul_lo_u32 v4, v2, v1
	v_add_u32_e32 v2, v4, v2
	v_cmp_ne_u32_e32 vcc, v3, v2
	s_and_saveexec_b64 s[6:7], vcc
	s_xor_b64 s[6:7], exec, s[6:7]
	s_cbranch_execz .LBB0_318
	s_waitcnt lgkmcnt(0)
	s_add_u32 s12, s94, 0x7500
	s_addc_u32 s13, s95, 0
	v_mov_b32_e32 v0, 0
	global_load_dword v0, v0, s[12:13] sc1
	s_waitcnt vmcnt(0)
	v_cmp_eq_u32_e32 vcc, v0, v1
	s_and_saveexec_b64 s[8:9], vcc
	s_cbranch_execz .LBB0_317
	s_add_u32 s10, s94, 0x4200
	s_addc_u32 s11, s95, 0
	s_mov_b32 s14, 1
	s_mov_b64 s[16:17], 0
	v_mov_b32_e32 v0, 0
	s_branch .LBB0_308

;     __device__ __forceinline__ const char* b(const Unit& u) const { return (const char*)Bt + (size_t)u.pn * 2 * hB() + (size_t)(u.pm >> gshift) * goff; }
;     __device__ __forceinline__ const char* b(const Unit& u) const { return (const char*)Bt + (size_t)((u.pn >> 4) * 4096 + (u.pn & 15) * 16) * 1024 * 2 + (size_t)(u.pm >> 1) * 512; }
;     __device__ __forceinline__ const char* b(const Unit& u) const { return (const char*)Bt + ((size_t)(((u.pm >> 4) * 1024 + u.pn * 256) * 16 + (u.pm & 15)) * 512) * 2; }
; __device__ __forceinline__ unsigned xb_add(unsigned* p, unsigned v) { return __hip_atomic_fetch_add(p, v, __ATOMIC_RELAXED, __HIP_MEMORY_SCOPE_AGENT); }
; __device__ __forceinline__ void xcd_barrier(const XcdBarrier& b, const int wave) {
;     ...
;             __builtin_amdgcn_fence(__ATOMIC_ACQUIRE, "agent");
;             xb_add(&bar[XB_XGEN(b.x)], 1u);
.LBB0_335:
	s_or_b64 exec, exec, s[6:7]
	s_mov_b64 s[6:7], exec
	v_mbcnt_lo_u32_b32 v0, s6, 0
	v_mbcnt_hi_u32_b32 v0, s7, v0
	v_cmp_eq_u32_e32 vcc, 0, v0
	s_waitcnt vmcnt(0)
	buffer_inv sc1
	s_and_saveexec_b64 s[8:9], vcc
	s_cbranch_execz .LBB0_337
	s_bcnt1_i32_b64 s6, s[6:7]
	v_mov_b32_e32 v0, 0x2000
	v_mov_b32_e32 v1, s6
.LBB0_337:
	s_or_b64 exec, exec, s[8:9]
	s_waitcnt vmcnt(0)

; #define AT_PK8(P, BASE, OUT) do { const unsigned a4 = pg8::pk_fp8x4((f32x4){P[BASE + 0], P[BASE + 1], P[BASE + 2], P[BASE + 3]}), b4 = pg8::pk_fp8x4((f32x4){P[BASE + 4], P[BASE + 5], P[BASE + 6], P[BASE + 7]}); \
;         auto r0 = __builtin_amdgcn_permlane32_swap(a4, b4, false, false); OUT = (long)(((unsigned long long)r0[1] << 32) | (unsigned long long)r0[0]); } while (0)
; __device__ __forceinline__ void attn_unit(const bool FINAL, const bool HN, LAS unsigned char* wl, const bf16_t* qb, const bf16_t* kb, const bf16_t* vb, int tq0, int dil, float sl, bf16x8 (&qr)[8], const bf16_t* nqb, const bf16_t* nkb, const bf16_t* nvb, int ntq0, int ndil, ...
;     ...
;         for (int r = 0; r < 16; ++r) { p[r] = __builtin_amdgcn_exp2f(p[r] - mn); ps += p[r]; }
;         { auto rr = __builtin_amdgcn_permlane32_swap(__float_as_uint(ps), __float_as_uint(ps), false, false); ps = __uint_as_float(rr[0]) + __uint_as_float(rr[1]); }
;         l_run = l_run * alpha + ps;
;         long pa0, pa1;
;     ...
;         AT_PK8(p, 0, pa0); AT_PK8(p, 8, pa1);
.LBB0_398:
	v_pk_add_f32 v[152:153], v[152:153], v[64:65] op_sel_hi:[1,0] neg_lo:[0,1] neg_hi:[0,1]
	v_pk_add_f32 v[154:155], v[154:155], v[64:65] op_sel_hi:[1,0] neg_lo:[0,1] neg_hi:[0,1]
	v_exp_f32_e32 v152, v152
	v_pk_add_f32 v[156:157], v[156:157], v[64:65] op_sel_hi:[1,0] neg_lo:[0,1] neg_hi:[0,1]
	v_exp_f32_e32 v153, v153
	v_pk_add_f32 v[160:161], v[160:161], v[64:65] op_sel_hi:[1,0] neg_lo:[0,1] neg_hi:[0,1]
	v_exp_f32_e32 v154, v154
	v_pk_add_f32 v[162:163], v[162:163], v[64:65] op_sel_hi:[1,0] neg_lo:[0,1] neg_hi:[0,1]
	v_exp_f32_e32 v155, v155
	v_pk_add_f32 v[166:167], v[166:167], v[64:65] op_sel_hi:[1,0] neg_lo:[0,1] neg_hi:[0,1]
	v_exp_f32_e32 v156, v156
	v_pk_add_f32 v[168:169], v[168:169], v[64:65] op_sel_hi:[1,0] neg_lo:[0,1] neg_hi:[0,1]
	v_exp_f32_e32 v157, v157
	v_pk_add_f32 v[170:171], v[170:171], v[64:65] op_sel_hi:[1,0] neg_lo:[0,1] neg_hi:[0,1]
	v_exp_f32_e32 v160, v160
	v_cvt_pk_fp8_f32 v68, v152, v153
	v_exp_f32_e32 v161, v161
	v_cvt_pk_fp8_f32 v68, v154, v155 op_sel:[0,0,1]
	v_exp_f32_e32 v162, v162
	v_pk_add_f32 v[72:73], v[152:153], v[154:155]
	v_exp_f32_e32 v163, v163
	v_cvt_pk_fp8_f32 v69, v156, v157
	v_exp_f32_e32 v166, v166
	v_cvt_pk_fp8_f32 v69, v160, v161 op_sel:[0,0,1]
	v_exp_f32_e32 v167, v167
	v_pk_add_f32 v[74:75], v[156:157], v[160:161]
	v_exp_f32_e32 v168, v168
	v_cvt_pk_fp8_f32 v70, v162, v163
	v_exp_f32_e32 v169, v169
	v_pk_add_f32 v[72:73], v[72:73], v[74:75]
	v_exp_f32_e32 v170, v170
	v_cvt_pk_fp8_f32 v70, v166, v167 op_sel:[0,0,1]
	v_exp_f32_e32 v171, v171
	v_pk_add_f32 v[76:77], v[162:163], v[166:167]
	v_cvt_pk_fp8_f32 v71, v168, v169
	s_nop 0
	v_cvt_pk_fp8_f32 v71, v170, v171 op_sel:[0,0,1]
	v_pk_add_f32 v[78:79], v[168:169], v[170:171]
	v_pk_add_f32 v[76:77], v[76:77], v[78:79]
	v_pk_add_f32 v[72:73], v[72:73], v[76:77]
	v_add_f32_e32 v65, v72, v73
	v_mov_b32_e32 v67, v65
	s_nop 1
	v_permlane32_swap_b32_e32 v65, v67
	v_permlane32_swap_b32_e32 v68, v69
	v_permlane32_swap_b32_e32 v70, v71
	s_mov_b64 s[6:7], -1
	s_and_b64 vcc, exec, s[72:73]
	s_cbranch_vccz .LBB0_400
	s_waitcnt vmcnt(0)
	s_mov_b64 s[6:7], 0

;     __device__ __forceinline__ const char* b(const Unit& u) const { return (const char*)Bt + (size_t)u.pn * 2 * hB() + (size_t)(u.pm >> gshift) * goff; }
;     __device__ __forceinline__ const char* b(const Unit& u) const { return (const char*)Bt + (size_t)((u.pn >> 4) * 4096 + (u.pn & 15) * 16) * 1024 * 2 + (size_t)(u.pm >> 1) * 512; }
;     __device__ __forceinline__ const char* b(const Unit& u) const { return (const char*)Bt + ((size_t)(((u.pm >> 4) * 1024 + u.pn * 256) * 16 + (u.pm & 15)) * 512) * 2; }
; __device__ __forceinline__ unsigned xb_add(unsigned* p, unsigned v) { return __hip_atomic_fetch_add(p, v, __ATOMIC_RELAXED, __HIP_MEMORY_SCOPE_AGENT); }
; __device__ __forceinline__ void xcd_barrier(const XcdBarrier& b, const int wave) {
;     ...
;             __builtin_amdgcn_fence(__ATOMIC_ACQUIRE, "agent");
;             xb_add(&bar[XB_XGEN(b.x)], 1u);
.LBB0_467:
	s_or_b64 exec, exec, s[8:9]
	s_mov_b64 s[8:9], exec
	v_mbcnt_lo_u32_b32 v0, s8, 0
	v_mbcnt_hi_u32_b32 v0, s9, v0
	v_cmp_eq_u32_e32 vcc, 0, v0
	s_waitcnt vmcnt(0)
	buffer_inv sc1
	s_and_saveexec_b64 s[10:11], vcc
	s_cbranch_execz .LBB0_469
	s_bcnt1_i32_b64 s8, s[8:9]
	v_mov_b32_e32 v0, 0x2000
	v_mov_b32_e32 v1, s8
.LBB0_469:
	s_or_b64 exec, exec, s[10:11]
	s_waitcnt vmcnt(0)

; #define AT_PK8(P, BASE, OUT) do { const unsigned a4 = pg8::pk_fp8x4((f32x4){P[BASE + 0], P[BASE + 1], P[BASE + 2], P[BASE + 3]}), b4 = pg8::pk_fp8x4((f32x4){P[BASE + 4], P[BASE + 5], P[BASE + 6], P[BASE + 7]}); \
;         auto r0 = __builtin_amdgcn_permlane32_swap(a4, b4, false, false); OUT = (long)(((unsigned long long)r0[1] << 32) | (unsigned long long)r0[0]); } while (0)
; __device__ __forceinline__ void attn_unit(const bool FINAL, const bool HN, LAS unsigned char* wl, const bf16_t* qb, const bf16_t* kb, const bf16_t* vb, int tq0, int dil, float sl, bf16x8 (&qr)[8], const bf16_t* nqb, const bf16_t* nkb, const bf16_t* nvb, int ntq0, int ndil, ...
;     ...
;         for (int r = 0; r < 16; ++r) { p[r] = __builtin_amdgcn_exp2f(p[r] - mn); ps += p[r]; }
;         { auto rr = __builtin_amdgcn_permlane32_swap(__float_as_uint(ps), __float_as_uint(ps), false, false); ps = __uint_as_float(rr[0]) + __uint_as_float(rr[1]); }
;         l_run = l_run * alpha + ps;
;         long pa0, pa1;
;     ...
;         AT_PK8(p, 0, pa0); AT_PK8(p, 8, pa1);
.LBB0_501:
	v_pk_add_f32 v[138:139], v[138:139], v[160:161] op_sel:[0,1] op_sel_hi:[1,1] neg_lo:[0,1] neg_hi:[0,1]
	v_pk_add_f32 v[140:141], v[140:141], v[160:161] op_sel:[0,1] op_sel_hi:[1,1] neg_lo:[0,1] neg_hi:[0,1]
	v_exp_f32_e32 v138, v138
	v_pk_add_f32 v[142:143], v[142:143], v[160:161] op_sel:[0,1] op_sel_hi:[1,1] neg_lo:[0,1] neg_hi:[0,1]
	v_exp_f32_e32 v139, v139
	v_pk_add_f32 v[144:145], v[144:145], v[160:161] op_sel:[0,1] op_sel_hi:[1,1] neg_lo:[0,1] neg_hi:[0,1]
	v_exp_f32_e32 v140, v140
	v_pk_add_f32 v[146:147], v[146:147], v[160:161] op_sel:[0,1] op_sel_hi:[1,1] neg_lo:[0,1] neg_hi:[0,1]
	v_exp_f32_e32 v141, v141
	v_pk_add_f32 v[150:151], v[150:151], v[160:161] op_sel:[0,1] op_sel_hi:[1,1] neg_lo:[0,1] neg_hi:[0,1]
	v_exp_f32_e32 v142, v142
	v_pk_add_f32 v[152:153], v[152:153], v[160:161] op_sel:[0,1] op_sel_hi:[1,1] neg_lo:[0,1] neg_hi:[0,1]
	v_exp_f32_e32 v143, v143
	v_pk_add_f32 v[154:155], v[154:155], v[160:161] op_sel:[0,1] op_sel_hi:[1,1] neg_lo:[0,1] neg_hi:[0,1]
	v_exp_f32_e32 v144, v144
	v_cvt_pk_fp8_f32 v66, v138, v139
	v_exp_f32_e32 v145, v145
	v_cvt_pk_fp8_f32 v66, v140, v141 op_sel:[0,0,1]
	v_exp_f32_e32 v146, v146
	v_pk_add_f32 v[70:71], v[138:139], v[140:141]
	v_exp_f32_e32 v147, v147
	v_cvt_pk_fp8_f32 v67, v142, v143
	v_exp_f32_e32 v150, v150
	v_cvt_pk_fp8_f32 v67, v144, v145 op_sel:[0,0,1]
	v_exp_f32_e32 v151, v151
	v_pk_add_f32 v[72:73], v[142:143], v[144:145]
	v_exp_f32_e32 v152, v152
	v_cvt_pk_fp8_f32 v68, v146, v147
	v_exp_f32_e32 v153, v153
	v_pk_add_f32 v[70:71], v[70:71], v[72:73]
	v_exp_f32_e32 v154, v154
	v_cvt_pk_fp8_f32 v68, v150, v151 op_sel:[0,0,1]
	v_exp_f32_e32 v155, v155
	v_pk_add_f32 v[74:75], v[146:147], v[150:151]
	v_cvt_pk_fp8_f32 v69, v152, v153
	s_nop 0
	v_cvt_pk_fp8_f32 v69, v154, v155 op_sel:[0,0,1]
	v_pk_add_f32 v[76:77], v[152:153], v[154:155]
	v_pk_add_f32 v[74:75], v[74:75], v[76:77]
	v_pk_add_f32 v[70:71], v[70:71], v[74:75]
	v_add_f32_e32 v142, v70, v71
	v_mov_b32_e32 v143, v142
	s_nop 1
	v_permlane32_swap_b32_e32 v142, v143
	v_permlane32_swap_b32_e32 v66, v67
	v_permlane32_swap_b32_e32 v68, v69
	s_mov_b64 s[4:5], -1
	s_and_b64 vcc, exec, s[78:79]
	s_cbranch_vccz .LBB0_503
	s_waitcnt vmcnt(0)
	s_mov_b64 s[4:5], 0

;     __device__ __forceinline__ const char* b(const Unit& u) const { return (const char*)Bt + (size_t)u.pn * 2 * hB() + (size_t)(u.pm >> gshift) * goff; }
;     __device__ __forceinline__ const char* b(const Unit& u) const { return (const char*)Bt + (size_t)((u.pn >> 4) * 4096 + (u.pn & 15) * 16) * 1024 * 2 + (size_t)(u.pm >> 1) * 512; }
;     __device__ __forceinline__ const char* b(const Unit& u) const { return (const char*)Bt + ((size_t)(((u.pm >> 4) * 1024 + u.pn * 256) * 16 + (u.pm & 15)) * 512) * 2; }
; __device__ __forceinline__ unsigned xb_add(unsigned* p, unsigned v) { return __hip_atomic_fetch_add(p, v, __ATOMIC_RELAXED, __HIP_MEMORY_SCOPE_AGENT); }
; __device__ __forceinline__ void xcd_barrier(const XcdBarrier& b, const int wave) {
;     ...
;             __builtin_amdgcn_fence(__ATOMIC_ACQUIRE, "agent");
;             xb_add(&bar[XB_XGEN(b.x)], 1u);
.LBB0_594:
	s_or_b64 exec, exec, s[6:7]
	s_mov_b64 s[6:7], exec
	v_mbcnt_lo_u32_b32 v0, s6, 0
	v_mbcnt_hi_u32_b32 v0, s7, v0
	v_cmp_eq_u32_e32 vcc, 0, v0
	s_waitcnt vmcnt(0)
	buffer_inv sc1
	s_and_saveexec_b64 s[8:9], vcc
	s_cbranch_execz .LBB0_596
	s_bcnt1_i32_b64 s6, s[6:7]
	v_mov_b32_e32 v0, 0x2000
	v_mov_b32_e32 v1, s6
.LBB0_596:
	s_or_b64 exec, exec, s[8:9]
	s_waitcnt vmcnt(0)

;     __device__ __forceinline__ const char* b(const Unit& u) const { return (const char*)Bt + (size_t)u.pn * 2 * hB() + (size_t)(u.pm >> gshift) * goff; }
;     __device__ __forceinline__ const char* b(const Unit& u) const { return (const char*)Bt + (size_t)((u.pn >> 4) * 4096 + (u.pn & 15) * 16) * 1024 * 2 + (size_t)(u.pm >> 1) * 512; }
;     __device__ __forceinline__ const char* b(const Unit& u) const { return (const char*)Bt + ((size_t)(((u.pm >> 4) * 1024 + u.pn * 256) * 16 + (u.pm & 15)) * 512) * 2; }
; __device__ __forceinline__ unsigned xb_ld(unsigned* p)              { return __hip_atomic_load(p, __ATOMIC_RELAXED, __HIP_MEMORY_SCOPE_AGENT); }
; __device__ __forceinline__ unsigned xb_add(unsigned* p, unsigned v) { return __hip_atomic_fetch_add(p, v, __ATOMIC_RELAXED, __HIP_MEMORY_SCOPE_AGENT); }
; #define XB_SPIN(cond, bar) do { unsigned _sp = 0; while (cond) { __builtin_amdgcn_s_sleep(1); \
;     if ((++_sp & 255u) == 0u) { if (xb_ld(&(bar)[XB_TMO])) break; if (_sp > XB_SPIN_CAP) { atomicAdd(&(bar)[XB_TMO], 1u); break; } } } } while (0)
; __device__ __forceinline__ void xcd_barrier(const XcdBarrier& b, const int wave) {
;     ...
;         const unsigned old = xb_add(&bar[XB_XSUB(b.x)], 1u);
;         const unsigned gen = old / nloc;
;         if (old + 1u == (gen + 1u) * nloc) {
;             __builtin_amdgcn_fence(__ATOMIC_RELEASE, "agent");
;             asm volatile("s_waitcnt vmcnt(0)" ::: "memory");
;             const unsigned og = xb_add(&bar[XB_TOP], 1u);
;             const unsigned tg = og / nx;
;             if (og + 1u == (tg + 1u) * nx) xb_add(&bar[XB_TOPGEN], 1u);
;             else XB_SPIN(xb_ld(&bar[XB_TOPGEN]) == tg, bar);
;             __builtin_amdgcn_fence(__ATOMIC_ACQUIRE, "agent");
;             xb_add(&bar[XB_XGEN(b.x)], 1u);
;             asm volatile("s_waitcnt vmcnt(0)" ::: "memory");
;         } else {
;             XB_SPIN(xb_ld(&bar[XB_XGEN(b.x)]) == gen, bar);
.LBB0_665:
	s_or_b64 exec, exec, s[8:9]
	v_cvt_f32_u32_e32 v4, v2
	s_waitcnt vmcnt(0)
	v_readfirstlane_b32 s6, v3
	v_sub_u32_e32 v3, 0, v2
	v_rcp_iflag_f32_e32 v4, v4
	v_add_u32_e32 v5, s6, v1
	v_mul_f32_e32 v4, 0x4f7ffffe, v4
	v_cvt_u32_f32_e32 v4, v4
	v_mul_lo_u32 v1, v3, v4
	v_mul_hi_u32 v1, v4, v1
	v_add_u32_e32 v1, v4, v1
	v_mul_hi_u32 v1, v5, v1
	v_mul_lo_u32 v3, v1, v2
	v_sub_u32_e32 v3, v5, v3
	v_add_u32_e32 v4, 1, v1
	v_cmp_ge_u32_e32 vcc, v3, v2
	s_nop 1
	v_cndmask_b32_e32 v1, v1, v4, vcc
	v_sub_u32_e32 v4, v3, v2
	v_cndmask_b32_e32 v3, v3, v4, vcc
	v_add_u32_e32 v4, 1, v1
	v_cmp_ge_u32_e32 vcc, v3, v2
	v_add_u32_e32 v3, 1, v5
	s_nop 0
	v_cndmask_b32_e32 v1, v1, v4, vcc
	v_mul_lo_u32 v4, v2, v1
	v_add_u32_e32 v2, v4, v2
	v_cmp_ne_u32_e32 vcc, v3, v2
	s_and_saveexec_b64 s[6:7], vcc
	s_xor_b64 s[6:7], exec, s[6:7]
	s_cbranch_execz .LBB0_679
	s_waitcnt lgkmcnt(0)
	s_add_u32 s12, s94, 0x7500
	s_addc_u32 s13, s95, 0
	v_mov_b32_e32 v0, 0
	global_load_dword v0, v0, s[12:13] sc1
	s_waitcnt vmcnt(0)
	v_cmp_eq_u32_e32 vcc, v0, v1
	s_and_saveexec_b64 s[8:9], vcc
	s_cbranch_execz .LBB0_678
	s_add_u32 s10, s94, 0x4200
	s_addc_u32 s11, s95, 0
	s_mov_b32 s24, 1
	s_mov_b64 s[14:15], 0
	v_mov_b32_e32 v0, 0
	s_branch .LBB0_669

;     __device__ __forceinline__ const char* b(const Unit& u) const { return (const char*)Bt + (size_t)u.pn * 2 * hB() + (size_t)(u.pm >> gshift) * goff; }
;     __device__ __forceinline__ const char* b(const Unit& u) const { return (const char*)Bt + (size_t)((u.pn >> 4) * 4096 + (u.pn & 15) * 16) * 1024 * 2 + (size_t)(u.pm >> 1) * 512; }
;     __device__ __forceinline__ const char* b(const Unit& u) const { return (const char*)Bt + ((size_t)(((u.pm >> 4) * 1024 + u.pn * 256) * 16 + (u.pm & 15)) * 512) * 2; }
; __device__ __forceinline__ unsigned xb_add(unsigned* p, unsigned v) { return __hip_atomic_fetch_add(p, v, __ATOMIC_RELAXED, __HIP_MEMORY_SCOPE_AGENT); }
; __device__ __forceinline__ void xcd_barrier(const XcdBarrier& b, const int wave) {
;     ...
;             __builtin_amdgcn_fence(__ATOMIC_ACQUIRE, "agent");
;             xb_add(&bar[XB_XGEN(b.x)], 1u);
.LBB0_696:
	s_or_b64 exec, exec, s[6:7]
	s_mov_b64 s[6:7], exec
	v_mbcnt_lo_u32_b32 v0, s6, 0
	v_mbcnt_hi_u32_b32 v0, s7, v0
	v_cmp_eq_u32_e32 vcc, 0, v0
	s_waitcnt vmcnt(0)
	buffer_inv sc1
	s_and_saveexec_b64 s[8:9], vcc
	s_cbranch_execz .LBB0_698
	s_bcnt1_i32_b64 s6, s[6:7]
	v_mov_b32_e32 v0, 0x2000
	v_mov_b32_e32 v1, s6
.LBB0_698:
	s_or_b64 exec, exec, s[8:9]
	s_waitcnt vmcnt(0)

; __global__ void __launch_bounds__(NWAVES * 64, 2) mk_fwd(Args args) {
;     ...
;     const bool fuse7 = G >= (T / 2 / 256) * (DM / 256);
;     for (int half = 0; half < 2; ++half) {
;         const size_t roff = (size_t)half * (T / 2);
;         bf16_t* const ab = (fuse7 && half) ? (bf16_t*)(ws + WS_XB) : abuf;
;         {
;             pg8::AddrStd g{h1b + roff * DM, wup, 2048, 2048, 30, 0u}; pg8::StaticOrder S; S.init(T / 2, DFF, G, (int)blockIdx.x, WGM_U);
;             pg8::EpiB<2, 2, false> E{ab, DFF, ssq1 + roff, nullptr, 0, 0, 1.f};
;             pg8::gemm_phase<pg8::EpiB<2, 2, false>, pg8::StaticOrder, pg8::AddrStd, true>(lds, 2048, g, S, E, wave);
;         }
;         xcd_barrier(bar, wave);
;         if (fuse7) {
;             pg8::AddrStd g{ab, wd, DFF, DFF, 30, 0u}; pg8::StaticOrder S; S.init(T / 2, 2048, G, (int)blockIdx.x, WGM_D);
;             pg8::EpiResOut E{h1b + roff * DM, (unsigned long long*)(ws + WS_SSQX) + roff, out + roff * DM, g_fin, (unsigned*)(ws + WS_CTL) + CW_BAR + XB_TMO, 2048, 32u};
;             pg8::gemm_phase<pg8::EpiResOut, pg8::StaticOrder, pg8::AddrStd, true>(lds, DFF, g, S, E, wave);
.LBB0_700:
	v_writelane_b32 v254, s66, 36
	s_add_u32 s0, s94, 0x60000
	s_mov_b32 s70, -1
	v_writelane_b32 v254, s67, 37
	v_writelane_b32 v254, s0, 38
	s_addc_u32 s0, s95, 0
	s_cmpk_gt_i32 s3, 0xff
	v_writelane_b32 v254, s0, 39
	s_cselect_b64 s[0:1], -1, 0
	v_writelane_b32 v254, s0, 40
	s_cmpk_lt_i32 s3, 0x100
	v_mov_b32_e32 v193, 0
	v_writelane_b32 v254, s1, 41
	s_cselect_b64 s[0:1], -1, 0
	v_writelane_b32 v254, s0, 42
	s_ashr_i32 s51, s2, 31
	v_mov_b32_e32 v227, 0x358637bd
	v_writelane_b32 v254, s1, 43
	s_lshr_b32 s0, s51, 29
	s_add_i32 s0, s2, s0
	s_ashr_i32 s20, s0, 3
	s_and_b32 s0, s0, -8
	s_sub_i32 s0, s2, s0
	s_lshl_b32 s1, s0, 7
	v_readlane_b32 s4, v254, 16
	s_cmp_eq_u32 s4, 1
	v_readlane_b32 s4, v254, 14
	s_cselect_b64 s[24:25], -1, 0
	s_cmpk_lt_u32 s4, 0x100
	s_cselect_b64 s[82:83], -1, 0
	s_ashr_i32 s49, s3, 31
	s_add_u32 s84, s94, 0x4200
	s_addc_u32 s85, s95, 0
	s_add_u32 s44, s94, 0x4400
	s_addc_u32 s45, s95, 0
	s_add_u32 s46, s94, 0x4500
	s_addc_u32 s47, s95, 0
	s_add_u32 s52, s94, 0x4600
	s_addc_u32 s53, s95, 0
	s_add_u32 s54, s94, 0x4700
	s_addc_u32 s55, s95, 0
	s_add_u32 s28, s94, 0x4800
	s_addc_u32 s29, s95, 0
	s_add_u32 s96, s94, 0x4900
	s_addc_u32 s97, s95, 0
	s_add_u32 s60, s94, 0x4a00
	s_addc_u32 s61, s95, 0
	s_add_u32 s58, s94, 0x4b00
	s_addc_u32 s59, s95, 0
	s_add_u32 s4, s94, 0x4c00
	s_addc_u32 s5, s95, 0
	s_add_u32 s6, s94, 0x4d00
	s_addc_u32 s7, s95, 0
	s_add_u32 s8, s94, 0x4e00
	s_addc_u32 s9, s95, 0
	s_add_u32 s10, s94, 0x4f00
	s_addc_u32 s11, s95, 0
	s_add_u32 s12, s94, 0x5000
	s_addc_u32 s13, s95, 0
	s_add_u32 s14, s94, 0x5100
	s_addc_u32 s15, s95, 0
	s_add_u32 s16, s94, 0x5200
	s_addc_u32 s17, s95, 0
	s_add_u32 s18, s94, 0x5300
	s_addc_u32 s19, s95, 0
	v_readlane_b32 s21, v254, 6
	s_cmp_eq_u32 s21, 15
	s_cselect_b64 s[22:23], -1, 0
	v_writelane_b32 v254, s22, 44
	s_cmp_eq_u32 s21, 14
	v_mov_b32_e32 v228, 1
	v_writelane_b32 v254, s23, 45
	s_cselect_b64 s[22:23], -1, 0
	v_writelane_b32 v254, s22, 46
	s_cmp_eq_u32 s21, 13
	s_movk_i32 s71, 0x1fff
	v_writelane_b32 v254, s23, 47
	s_cselect_b64 s[22:23], -1, 0
	v_writelane_b32 v254, s22, 48
	s_cmp_eq_u32 s21, 12
	v_mov_b64_e32 v[194:195], 0x400
	v_writelane_b32 v254, s23, 49
	s_cselect_b64 s[22:23], -1, 0
	v_writelane_b32 v254, s22, 50
	s_cmp_eq_u32 s21, 11
	v_mov_b64_e32 v[196:197], 0x3ff
	v_writelane_b32 v254, s23, 51
	s_cselect_b64 s[22:23], -1, 0
	v_writelane_b32 v254, s22, 52
	s_cmp_eq_u32 s21, 10
	v_mov_b64_e32 v[198:199], 0x100
	v_writelane_b32 v254, s23, 53
	s_cselect_b64 s[22:23], -1, 0
	v_writelane_b32 v254, s22, 54
	s_cmp_eq_u32 s21, 9
	v_mov_b64_e32 v[200:201], 0xff
	v_writelane_b32 v254, s23, 55
	s_cselect_b64 s[22:23], -1, 0
	v_writelane_b32 v254, s22, 56
	s_cmp_eq_u32 s21, 8
	v_mbcnt_hi_u32_b32 v229, -1, v253
	v_writelane_b32 v254, s23, 57
	s_cselect_b64 s[22:23], -1, 0
	v_writelane_b32 v254, s22, 58
	s_cmp_eq_u32 s21, 7
	s_mov_b32 s72, 0x46800000
	v_writelane_b32 v254, s23, 59
	s_cselect_b64 s[22:23], -1, 0
	v_writelane_b32 v254, s22, 60
	s_cmp_eq_u32 s21, 6
	s_mov_b64 s[78:79], 0
	v_writelane_b32 v254, s23, 61
	s_cselect_b64 s[22:23], -1, 0
	v_writelane_b32 v254, s22, 62
	s_cmp_eq_u32 s21, 5
	s_waitcnt lgkmcnt(0)
	v_writelane_b32 v254, s23, 63
	s_cselect_b64 s[22:23], -1, 0
	v_writelane_b32 v255, s22, 0
	s_cmp_eq_u32 s21, 4
	s_barrier
; __global__ void __launch_bounds__(NWAVES * 64, 2) mk_fwd(Args args) {
;     ...
;     for (int half = 0; half < 2; ++half) {
;         const size_t roff = (size_t)half * (T / 2);
;         bf16_t* const ab = (fuse7 && half) ? (bf16_t*)(ws + WS_XB) : abuf;
;         {
;             pg8::AddrStd g{h1b + roff * DM, wup, 2048, 2048, 30, 0u}; pg8::StaticOrder S; S.init(T / 2, DFF, G, (int)blockIdx.x, WGM_U);
;             pg8::EpiB<2, 2, false> E{ab, DFF, ssq1 + roff, nullptr, 0, 0, 1.f};
;             pg8::gemm_phase<pg8::EpiB<2, 2, false>, pg8::StaticOrder, pg8::AddrStd, true>(lds, 2048, g, S, E, wave);
;         }
;         xcd_barrier(bar, wave);
;         if (fuse7) {
;             pg8::AddrStd g{ab, wd, DFF, DFF, 30, 0u}; pg8::StaticOrder S; S.init(T / 2, 2048, G, (int)blockIdx.x, WGM_D);
;             pg8::EpiResOut E{h1b + roff * DM, (unsigned long long*)(ws + WS_SSQX) + roff, out + roff * DM, g_fin, (unsigned*)(ws + WS_CTL) + CW_BAR + XB_TMO, 2048, 32u};
;             pg8::gemm_phase<pg8::EpiResOut, pg8::StaticOrder, pg8::AddrStd, true>(lds, DFF, g, S, E, wave);
	v_writelane_b32 v255, s23, 1
	s_cselect_b64 s[22:23], -1, 0
	v_writelane_b32 v255, s22, 2
	s_cmp_eq_u32 s21, 3
	s_nop 0
	v_writelane_b32 v255, s23, 3
	s_cselect_b64 s[22:23], -1, 0
	v_writelane_b32 v255, s22, 4
	s_cmp_eq_u32 s21, 2
	s_nop 0
	v_writelane_b32 v255, s23, 5
	s_cselect_b64 s[22:23], -1, 0
	v_writelane_b32 v255, s22, 6
	s_cmp_eq_u32 s21, 1
	s_nop 0
	v_writelane_b32 v255, s23, 7
	s_cselect_b64 s[22:23], -1, 0
	v_writelane_b32 v255, s22, 8
	s_cmp_eq_u32 s21, 0
	s_nop 0
	v_writelane_b32 v255, s23, 9
	s_cselect_b64 s[22:23], -1, 0
	s_lshl_b32 s21, s21, 8
	v_writelane_b32 v255, s22, 10
	s_add_u32 s21, s88, s21
	s_nop 0
	v_writelane_b32 v255, s23, 11
	s_addc_u32 s22, s89, 0
	s_add_u32 s26, s21, 0x1400
	s_addc_u32 s27, s22, 0
	v_writelane_b32 v255, s26, 12
	s_nop 1
	v_writelane_b32 v255, s27, 13
	s_add_u32 s26, s94, 0x7500
	s_addc_u32 s27, s95, 0
	s_add_u32 s22, s94, 0x7400
	s_addc_u32 s23, s95, 0
	v_writelane_b32 v255, s22, 14
	v_writelane_b32 v254, s26, 32
	s_nop 0
	v_writelane_b32 v255, s23, 15
	s_add_u32 s22, s94, 0x7500
	v_writelane_b32 v254, s27, 33
	s_addc_u32 s23, s95, 0
	v_writelane_b32 v254, s22, 14
	s_lshl_b32 s21, s0, 5
	s_nop 0
	v_writelane_b32 v254, s23, 15
	s_add_u32 s22, s94, 0x80000
	v_writelane_b32 v255, s22, 16
	s_addc_u32 s22, s95, 0
	v_writelane_b32 v255, s22, 17
	s_cmp_lt_i32 s0, 0
	s_mul_i32 s22, s0, 0x81
	s_cselect_b32 s1, s22, s1
	s_mul_i32 s0, s0, 33
	s_cselect_b32 s21, s0, s21
	s_add_i32 s0, s1, s20
	s_ashr_i32 s1, s0, 31
	s_lshr_b32 s1, s1, 25
	s_add_i32 s1, s0, s1
	s_and_b32 s22, s1, 0xff80
	s_sub_i32 s0, s0, s22
	s_bfe_i32 s22, s0, 0x80000
	s_bfe_u32 s22, s22, 0x2000d
	s_add_i32 s22, s0, s22
	s_and_b32 s23, s22, 0xfc
	s_sub_i32 s0, s0, s23
	s_ashr_i32 s1, s1, 7
	s_bfe_i32 s22, s22, 0x80000
	s_lshl_b32 s1, s1, 2
	s_sext_i32_i16 s22, s22
	s_sext_i32_i8 s0, s0
	s_add_i32 s26, s1, s0
	s_ashr_i32 s0, s22, 2
	v_writelane_b32 v255, s0, 18
	s_lshr_b32 s0, s22, 2
	s_mov_b32 s22, s26
	s_ashr_i32 s27, s26, 31
	s_bfe_i64 s[0:1], s[0:1], 0x100000
	v_writelane_b32 v255, s22, 19
	s_lshl_b64 s[0:1], s[0:1], 20
	v_writelane_b32 v254, s24, 26
	v_writelane_b32 v255, s23, 20
	s_lshl_b64 s[22:23], s[26:27], 20
	s_add_u32 s0, s64, s0
	v_writelane_b32 v255, s22, 21
	s_addc_u32 s1, s65, s1
	v_writelane_b32 v254, s25, 27
	v_writelane_b32 v255, s23, 22
	s_add_u32 s22, s0, 0x80000
	s_addc_u32 s23, s1, 0
	v_writelane_b32 v255, s22, 23
	v_cndmask_b32_e64 v226, 0, 1, s[24:25]
	s_nop 0
	v_writelane_b32 v255, s23, 24
	s_add_u32 s22, s0, 0x80080
	v_writelane_b32 v255, s0, 25
	s_addc_u32 s23, s1, 0
	s_nop 0
	v_writelane_b32 v255, s1, 26
	s_add_i32 s0, s21, s20
	s_ashr_i32 s1, s0, 31
	s_lshr_b32 s1, s1, 27
	s_add_i32 s1, s0, s1
	s_and_b32 s20, s1, 0xffe0
	s_sub_i32 s0, s0, s20
	s_bfe_i32 s20, s0, 0x80000
	s_bfe_u32 s20, s20, 0x2000d
	s_add_i32 s20, s0, s20
	s_and_b32 s21, s20, 0xfc
	s_sub_i32 s0, s0, s21
	s_ashr_i32 s1, s1, 5
	s_bfe_i32 s20, s20, 0x80000
	v_writelane_b32 v255, s22, 27
	s_lshl_b32 s1, s1, 2
	s_sext_i32_i16 s20, s20
	s_sext_i32_i8 s0, s0
	v_writelane_b32 v255, s23, 28
	s_add_i32 s22, s1, s0
	s_ashr_i32 s0, s20, 2
	v_writelane_b32 v255, s0, 29
	s_lshr_b32 s0, s20, 2
	s_mov_b32 s20, s22
	s_ashr_i32 s23, s22, 31
	s_bfe_i64 s[0:1], s[0:1], 0x100000
	v_writelane_b32 v255, s20, 30
	s_lshl_b64 s[0:1], s[0:1], 22
	s_nop 0
	v_writelane_b32 v255, s21, 31
	s_lshl_b64 s[20:21], s[22:23], 22
	s_add_u32 s0, s62, s0
	s_addc_u32 s1, s63, s1
	s_add_u32 s22, s0, 0x200000
	s_addc_u32 s23, s1, 0
	v_writelane_b32 v255, s22, 32
	s_nop 1
	v_writelane_b32 v255, s23, 33
	s_add_u32 s22, s68, s20
	v_writelane_b32 v255, s20, 34
	s_addc_u32 s23, s69, s21
	s_nop 0
	v_writelane_b32 v255, s21, 35
	s_add_u32 s20, s22, 0x200000
	v_writelane_b32 v255, s22, 36
	s_addc_u32 s21, s23, 0
	s_nop 0
	v_writelane_b32 v255, s23, 37
	v_writelane_b32 v255, s20, 38
	s_nop 1
	v_writelane_b32 v255, s21, 39
	s_add_u32 s20, s0, 0x200080
	v_writelane_b32 v255, s0, 40
	s_addc_u32 s21, s1, 0
	s_nop 0
	v_writelane_b32 v255, s1, 41
	v_writelane_b32 v255, s20, 42
	s_add_i32 s0, 0, 0x20160
	s_nop 0
	v_writelane_b32 v255, s21, 43
	v_writelane_b32 v255, s0, 44
	s_add_i32 s0, 0, 0x20164
	v_writelane_b32 v255, s0, 45
	v_writelane_b32 v255, s44, 46
	s_mov_b64 s[0:1], -1
	v_writelane_b32 v254, s0, 10
	v_writelane_b32 v255, s45, 47
	v_writelane_b32 v255, s46, 48
	v_writelane_b32 v254, s1, 11
	s_mov_b64 s[20:21], 0
	v_writelane_b32 v255, s47, 49
	v_readlane_b32 s95, v254, 18
	v_writelane_b32 v254, s74, 6
	v_writelane_b32 v255, s52, 50
	s_nop 0
	v_writelane_b32 v254, s75, 7
	v_writelane_b32 v255, s53, 51
	v_writelane_b32 v255, s54, 52
	v_writelane_b32 v254, s28, 16
	s_nop 0
	v_writelane_b32 v255, s55, 53
	v_writelane_b32 v254, s29, 17
	s_branch .LBB0_703

;     __device__ __forceinline__ const char* b(const Unit& u) const { return (const char*)Bt + (size_t)u.pn * 2 * hB() + (size_t)(u.pm >> gshift) * goff; }
;     __device__ __forceinline__ const char* b(const Unit& u) const { return (const char*)Bt + (size_t)((u.pn >> 4) * 4096 + (u.pn & 15) * 16) * 1024 * 2 + (size_t)(u.pm >> 1) * 512; }
;     __device__ __forceinline__ const char* b(const Unit& u) const { return (const char*)Bt + ((size_t)(((u.pm >> 4) * 1024 + u.pn * 256) * 16 + (u.pm & 15)) * 512) * 2; }
; __device__ __forceinline__ unsigned xb_add(unsigned* p, unsigned v) { return __hip_atomic_fetch_add(p, v, __ATOMIC_RELAXED, __HIP_MEMORY_SCOPE_AGENT); }
; __device__ __forceinline__ void xcd_barrier(const XcdBarrier& b, const int wave) {
;     ...
;             __builtin_amdgcn_fence(__ATOMIC_ACQUIRE, "agent");
;             xb_add(&bar[XB_XGEN(b.x)], 1u);
.LBB0_773:
	s_or_b64 exec, exec, s[22:23]
	s_mov_b64 s[22:23], exec
	v_mbcnt_lo_u32_b32 v0, s22, 0
	v_mbcnt_hi_u32_b32 v0, s23, v0
	v_cmp_eq_u32_e32 vcc, 0, v0
	s_waitcnt vmcnt(0)
	buffer_inv sc1
	s_and_saveexec_b64 s[24:25], vcc
	s_cbranch_execz .LBB0_775
	s_bcnt1_i32_b64 s0, s[22:23]
	v_mov_b32_e32 v0, s0
	v_readlane_b32 s0, v254, 32
	v_readlane_b32 s1, v254, 33
	s_nop 4
.LBB0_775:
	s_or_b64 exec, exec, s[24:25]
	s_waitcnt vmcnt(0)

;     __device__ __forceinline__ const char* b(const Unit& u) const { return (const char*)Bt + (size_t)u.pn * 2 * hB() + (size_t)(u.pm >> gshift) * goff; }
;     __device__ __forceinline__ const char* b(const Unit& u) const { return (const char*)Bt + (size_t)((u.pn >> 4) * 4096 + (u.pn & 15) * 16) * 1024 * 2 + (size_t)(u.pm >> 1) * 512; }
;     __device__ __forceinline__ const char* b(const Unit& u) const { return (const char*)Bt + ((size_t)(((u.pm >> 4) * 1024 + u.pn * 256) * 16 + (u.pm & 15)) * 512) * 2; }
; __device__ __forceinline__ unsigned xb_add(unsigned* p, unsigned v) { return __hip_atomic_fetch_add(p, v, __ATOMIC_RELAXED, __HIP_MEMORY_SCOPE_AGENT); }
; __device__ __forceinline__ void xcd_barrier(const XcdBarrier& b, const int wave) {
;     ...
;             __builtin_amdgcn_fence(__ATOMIC_ACQUIRE, "agent");
;             xb_add(&bar[XB_XGEN(b.x)], 1u);
.LBB0_864:
	s_or_b64 exec, exec, s[22:23]
	s_mov_b64 s[22:23], exec
	v_mbcnt_lo_u32_b32 v0, s22, 0
	v_mbcnt_hi_u32_b32 v0, s23, v0
	v_cmp_eq_u32_e32 vcc, 0, v0
	s_waitcnt vmcnt(0)
	buffer_inv sc1
	s_and_saveexec_b64 s[24:25], vcc
	s_cbranch_execz .LBB0_866
	s_bcnt1_i32_b64 s0, s[22:23]
	v_mov_b32_e32 v0, s0
	v_readlane_b32 s0, v254, 32
	v_readlane_b32 s1, v254, 33
	s_nop 4
.LBB0_866:
	s_or_b64 exec, exec, s[24:25]
	s_waitcnt vmcnt(0)
